# out-projection GEMM main loop: M0 offsets with one scalar add; K stepping (SALU and the two lane-offset adds) behind the last compute segment's MFMAs
# speedup vs baseline: 1.0018x; 1.0018x over previous
.LBB0_1259:
	s_add_u32 s22, s92, s76
	s_addc_u32 s23, s93, s77
	s_add_u32 s80, s96, s76
	s_addc_u32 s81, s97, s77
	s_cmp_eq_u32 s44, 0
	s_cselect_b32 s23, s15, s23
	s_cselect_b32 s22, s91, s22
	s_cselect_b32 vcc_hi, s89, s81
	s_cselect_b32 vcc_lo, s8, s80
	s_add_u32 s80, s92, s76
	s_addc_u32 s81, s93, s77
	s_sub_u32 s80, s80, 0x80
	s_subb_u32 s81, s81, 0
	ds_read_b128 v[142:145], v222
	ds_read_b128 v[146:149], v222 offset:1024
	ds_read_b128 v[150:153], v222 offset:2048
	ds_read_b128 v[154:157], v222 offset:3072
	ds_read_b128 v[158:161], v223
	ds_read_b128 v[162:165], v223 offset:1024
	ds_read_b128 v[166:169], v223 offset:2048
	ds_read_b128 v[170:173], v223 offset:3072
	s_mov_b32 m0, s9
	ds_read_b128 v[174:177], v140
	ds_read_b128 v[178:181], v140 offset:1024
	ds_read_b128 v[182:185], v140 offset:2048
	ds_read_b128 v[186:189], v140 offset:3072
	ds_read_b128 v[190:193], v140 offset:4096
	ds_read_b128 v[194:197], v140 offset:5120
	ds_read_b128 v[198:201], v140 offset:6144
	ds_read_b128 v[202:205], v140 offset:7168
	global_load_lds_dwordx4 v208, s[80:81]
	s_mov_b32 m0, s12
	s_nop 0
	global_load_lds_dwordx4 v128, s[80:81]
	s_add_i32 m0, s45, 0xc000
	s_nop 0
	global_load_lds_dwordx4 v136, s[92:93]
	s_add_i32 m0, s45, 0xe000
	s_nop 0
	global_load_lds_dwordx4 v134, s[92:93]
	s_waitcnt vmcnt(8)
	s_waitcnt lgkmcnt(0)
	s_barrier
	v_mfma_f32_16x16x32_bf16 v[124:127], v[142:145], v[174:177], v[124:127]
	v_mfma_f32_16x16x32_bf16 v[120:123], v[150:153], v[174:177], v[120:123]
	v_mfma_f32_16x16x32_bf16 v[108:111], v[142:145], v[182:185], v[108:111]
	v_mfma_f32_16x16x32_bf16 v[104:107], v[150:153], v[182:185], v[104:107]
	v_mfma_f32_16x16x32_bf16 v[92:95], v[142:145], v[190:193], v[92:95]
	v_mfma_f32_16x16x32_bf16 v[88:91], v[150:153], v[190:193], v[88:91]
	v_mfma_f32_16x16x32_bf16 v[76:79], v[142:145], v[198:201], v[76:79]
	v_mfma_f32_16x16x32_bf16 v[72:75], v[150:153], v[198:201], v[72:75]
	v_mfma_f32_16x16x32_bf16 v[124:127], v[146:149], v[178:181], v[124:127]
	v_mfma_f32_16x16x32_bf16 v[120:123], v[154:157], v[178:181], v[120:123]
	v_mfma_f32_16x16x32_bf16 v[108:111], v[146:149], v[186:189], v[108:111]
	v_mfma_f32_16x16x32_bf16 v[104:107], v[154:157], v[186:189], v[104:107]
	v_mfma_f32_16x16x32_bf16 v[92:95], v[146:149], v[194:197], v[92:95]
	v_mfma_f32_16x16x32_bf16 v[88:91], v[154:157], v[194:197], v[88:91]
	v_mfma_f32_16x16x32_bf16 v[76:79], v[146:149], v[202:205], v[76:79]
	v_mfma_f32_16x16x32_bf16 v[72:75], v[154:157], v[202:205], v[72:75]
	v_mfma_f32_16x16x32_bf16 v[116:119], v[158:161], v[174:177], v[116:119]
	v_mfma_f32_16x16x32_bf16 v[112:115], v[166:169], v[174:177], v[112:115]
	v_mfma_f32_16x16x32_bf16 v[100:103], v[158:161], v[182:185], v[100:103]
	v_mfma_f32_16x16x32_bf16 v[96:99], v[166:169], v[182:185], v[96:99]
	v_mfma_f32_16x16x32_bf16 v[84:87], v[158:161], v[190:193], v[84:87]
	v_mfma_f32_16x16x32_bf16 v[80:83], v[166:169], v[190:193], v[80:83]
	v_mfma_f32_16x16x32_bf16 v[68:71], v[158:161], v[198:201], v[68:71]
	v_mfma_f32_16x16x32_bf16 v[64:67], v[166:169], v[198:201], v[64:67]
	v_mfma_f32_16x16x32_bf16 v[116:119], v[162:165], v[178:181], v[116:119]
	v_mfma_f32_16x16x32_bf16 v[112:115], v[170:173], v[178:181], v[112:115]
	v_mfma_f32_16x16x32_bf16 v[100:103], v[162:165], v[186:189], v[100:103]
	v_mfma_f32_16x16x32_bf16 v[96:99], v[170:173], v[186:189], v[96:99]
	v_mfma_f32_16x16x32_bf16 v[84:87], v[162:165], v[194:197], v[84:87]
	v_mfma_f32_16x16x32_bf16 v[80:83], v[170:173], v[194:197], v[80:83]
	v_mfma_f32_16x16x32_bf16 v[68:71], v[162:165], v[202:205], v[68:71]
	v_mfma_f32_16x16x32_bf16 v[64:67], v[170:173], v[202:205], v[64:67]
	s_barrier
	s_add_i32 m0, s43, 0x10000
	ds_read_b128 v[174:177], v140 offset:16384
	ds_read_b128 v[178:181], v140 offset:17408
	ds_read_b128 v[182:185], v140 offset:18432
	ds_read_b128 v[186:189], v140 offset:19456
	ds_read_b128 v[190:193], v140 offset:20480
	ds_read_b128 v[194:197], v140 offset:21504
	ds_read_b128 v[198:201], v140 offset:22528
	ds_read_b128 v[202:205], v140 offset:23552
	global_load_lds_dwordx4 v208, vcc
	s_add_i32 m0, s43, 0x12000
	s_add_u32 s80, vcc_lo, 0x80000
	s_addc_u32 s81, vcc_hi, 0
	global_load_lds_dwordx4 v128, vcc
	s_add_i32 m0, s43, 0x14000
	s_nop 0
	global_load_lds_dwordx4 v208, s[80:81]
	s_add_i32 m0, s43, 0x16000
	s_nop 0
	global_load_lds_dwordx4 v128, s[80:81]
	s_waitcnt vmcnt(6)
	s_waitcnt lgkmcnt(0)
	s_barrier
	v_mfma_f32_16x16x32_bf16 v[60:63], v[142:145], v[174:177], v[60:63]
	v_mfma_f32_16x16x32_bf16 v[56:59], v[150:153], v[174:177], v[56:59]
	v_mfma_f32_16x16x32_bf16 v[44:47], v[142:145], v[182:185], v[44:47]
	v_mfma_f32_16x16x32_bf16 v[40:43], v[150:153], v[182:185], v[40:43]
	v_mfma_f32_16x16x32_bf16 v[28:31], v[142:145], v[190:193], v[28:31]
	v_mfma_f32_16x16x32_bf16 v[24:27], v[150:153], v[190:193], v[24:27]
	v_mfma_f32_16x16x32_bf16 v[12:15], v[142:145], v[198:201], v[12:15]
	v_mfma_f32_16x16x32_bf16 v[8:11], v[150:153], v[198:201], v[8:11]
	v_mfma_f32_16x16x32_bf16 v[60:63], v[146:149], v[178:181], v[60:63]
	v_mfma_f32_16x16x32_bf16 v[56:59], v[154:157], v[178:181], v[56:59]
	v_mfma_f32_16x16x32_bf16 v[44:47], v[146:149], v[186:189], v[44:47]
	v_mfma_f32_16x16x32_bf16 v[40:43], v[154:157], v[186:189], v[40:43]
	v_mfma_f32_16x16x32_bf16 v[28:31], v[146:149], v[194:197], v[28:31]
	v_mfma_f32_16x16x32_bf16 v[24:27], v[154:157], v[194:197], v[24:27]
	v_mfma_f32_16x16x32_bf16 v[12:15], v[146:149], v[202:205], v[12:15]
	v_mfma_f32_16x16x32_bf16 v[8:11], v[154:157], v[202:205], v[8:11]
	v_mfma_f32_16x16x32_bf16 v[52:55], v[158:161], v[174:177], v[52:55]
	v_mfma_f32_16x16x32_bf16 v[48:51], v[166:169], v[174:177], v[48:51]
	v_mfma_f32_16x16x32_bf16 v[36:39], v[158:161], v[182:185], v[36:39]
	v_mfma_f32_16x16x32_bf16 v[32:35], v[166:169], v[182:185], v[32:35]
	v_mfma_f32_16x16x32_bf16 v[20:23], v[158:161], v[190:193], v[20:23]
	v_mfma_f32_16x16x32_bf16 v[16:19], v[166:169], v[190:193], v[16:19]
	v_mfma_f32_16x16x32_bf16 v[4:7], v[158:161], v[198:201], v[4:7]
	v_mfma_f32_16x16x32_bf16 v[0:3], v[166:169], v[198:201], v[0:3]
	v_mfma_f32_16x16x32_bf16 v[52:55], v[162:165], v[178:181], v[52:55]
	v_mfma_f32_16x16x32_bf16 v[48:51], v[170:173], v[178:181], v[48:51]
	v_mfma_f32_16x16x32_bf16 v[36:39], v[162:165], v[186:189], v[36:39]
	v_mfma_f32_16x16x32_bf16 v[32:35], v[170:173], v[186:189], v[32:35]
	v_mfma_f32_16x16x32_bf16 v[20:23], v[162:165], v[194:197], v[20:23]
	v_mfma_f32_16x16x32_bf16 v[16:19], v[170:173], v[194:197], v[16:19]
	v_mfma_f32_16x16x32_bf16 v[4:7], v[162:165], v[202:205], v[4:7]
	v_mfma_f32_16x16x32_bf16 v[0:3], v[170:173], v[202:205], v[0:3]
	s_barrier
	ds_read_b128 v[142:145], v224
	ds_read_b128 v[146:149], v224 offset:1024
	ds_read_b128 v[150:153], v224 offset:2048
	ds_read_b128 v[154:157], v224 offset:3072
	ds_read_b128 v[158:161], v225
	ds_read_b128 v[162:165], v225 offset:1024
	ds_read_b128 v[166:169], v225 offset:2048
	ds_read_b128 v[170:173], v225 offset:3072
	ds_read_b128 v[174:177], v140 offset:32768
	ds_read_b128 v[178:181], v140 offset:33792
	ds_read_b128 v[182:185], v140 offset:34816
	ds_read_b128 v[186:189], v140 offset:35840
	ds_read_b128 v[190:193], v140 offset:36864
	ds_read_b128 v[194:197], v140 offset:37888
	ds_read_b128 v[198:201], v140 offset:38912
	ds_read_b128 v[202:205], v140 offset:39936
	s_mov_b32 m0, s45
	s_nop 0
	global_load_lds_dwordx4 v208, s[22:23]
	s_mov_b32 m0, s52
	s_nop 0
	global_load_lds_dwordx4 v128, s[22:23]
	s_mov_b32 m0, s53
	s_add_u32 s22, s22, 0x80000
	s_addc_u32 s23, s23, 0
	global_load_lds_dwordx4 v208, s[22:23]
	s_mov_b32 m0, s85
	s_nop 0
	global_load_lds_dwordx4 v128, s[22:23]
	s_waitcnt vmcnt(8)
	s_waitcnt lgkmcnt(0)
	s_barrier
	v_mfma_f32_16x16x32_bf16 v[124:127], v[142:145], v[174:177], v[124:127]
	v_mfma_f32_16x16x32_bf16 v[120:123], v[150:153], v[174:177], v[120:123]
	v_mfma_f32_16x16x32_bf16 v[108:111], v[142:145], v[182:185], v[108:111]
	v_mfma_f32_16x16x32_bf16 v[104:107], v[150:153], v[182:185], v[104:107]
	v_mfma_f32_16x16x32_bf16 v[92:95], v[142:145], v[190:193], v[92:95]
	v_mfma_f32_16x16x32_bf16 v[88:91], v[150:153], v[190:193], v[88:91]
	v_mfma_f32_16x16x32_bf16 v[76:79], v[142:145], v[198:201], v[76:79]
	v_mfma_f32_16x16x32_bf16 v[72:75], v[150:153], v[198:201], v[72:75]
	v_mfma_f32_16x16x32_bf16 v[124:127], v[146:149], v[178:181], v[124:127]
	v_mfma_f32_16x16x32_bf16 v[120:123], v[154:157], v[178:181], v[120:123]
	v_mfma_f32_16x16x32_bf16 v[108:111], v[146:149], v[186:189], v[108:111]
	v_mfma_f32_16x16x32_bf16 v[104:107], v[154:157], v[186:189], v[104:107]
	v_mfma_f32_16x16x32_bf16 v[92:95], v[146:149], v[194:197], v[92:95]
	v_mfma_f32_16x16x32_bf16 v[88:91], v[154:157], v[194:197], v[88:91]
	v_mfma_f32_16x16x32_bf16 v[76:79], v[146:149], v[202:205], v[76:79]
	v_mfma_f32_16x16x32_bf16 v[72:75], v[154:157], v[202:205], v[72:75]
	v_mfma_f32_16x16x32_bf16 v[116:119], v[158:161], v[174:177], v[116:119]
	v_mfma_f32_16x16x32_bf16 v[112:115], v[166:169], v[174:177], v[112:115]
	v_mfma_f32_16x16x32_bf16 v[100:103], v[158:161], v[182:185], v[100:103]
	v_mfma_f32_16x16x32_bf16 v[96:99], v[166:169], v[182:185], v[96:99]
	v_mfma_f32_16x16x32_bf16 v[84:87], v[158:161], v[190:193], v[84:87]
	v_mfma_f32_16x16x32_bf16 v[80:83], v[166:169], v[190:193], v[80:83]
	v_mfma_f32_16x16x32_bf16 v[68:71], v[158:161], v[198:201], v[68:71]
	v_mfma_f32_16x16x32_bf16 v[64:67], v[166:169], v[198:201], v[64:67]
	v_mfma_f32_16x16x32_bf16 v[116:119], v[162:165], v[178:181], v[116:119]
	v_mfma_f32_16x16x32_bf16 v[112:115], v[170:173], v[178:181], v[112:115]
	v_mfma_f32_16x16x32_bf16 v[100:103], v[162:165], v[186:189], v[100:103]
	v_mfma_f32_16x16x32_bf16 v[96:99], v[170:173], v[186:189], v[96:99]
	v_mfma_f32_16x16x32_bf16 v[84:87], v[162:165], v[194:197], v[84:87]
	v_mfma_f32_16x16x32_bf16 v[80:83], v[170:173], v[194:197], v[80:83]
	v_mfma_f32_16x16x32_bf16 v[68:71], v[162:165], v[202:205], v[68:71]
	v_mfma_f32_16x16x32_bf16 v[64:67], v[170:173], v[202:205], v[64:67]
	s_barrier
	s_add_i32 m0, s43, 0x17f80
	ds_read_b128 v[174:177], v140 offset:49152
	ds_read_b128 v[178:181], v140 offset:50176
	ds_read_b128 v[182:185], v140 offset:51200
	ds_read_b128 v[186:189], v140 offset:52224
	ds_read_b128 v[190:193], v140 offset:53248
	ds_read_b128 v[194:197], v140 offset:54272
	ds_read_b128 v[198:201], v140 offset:55296
	ds_read_b128 v[202:205], v140 offset:56320
	global_load_lds_dwordx4 v208, vcc offset:128
	s_add_i32 m0, s43, 0x19f80
	s_add_u32 s22, vcc_lo, 0x80080
	s_addc_u32 s23, vcc_hi, 0
	global_load_lds_dwordx4 v128, vcc offset:128
	s_add_i32 m0, s43, 0x1c000
	s_nop 0
	global_load_lds_dwordx4 v208, s[22:23]
	s_add_i32 m0, s43, 0x1e000
	s_nop 0
	global_load_lds_dwordx4 v128, s[22:23]
	s_waitcnt vmcnt(6)
	s_waitcnt lgkmcnt(0)
	s_barrier
	v_mfma_f32_16x16x32_bf16 v[60:63], v[142:145], v[174:177], v[60:63]
	v_mfma_f32_16x16x32_bf16 v[56:59], v[150:153], v[174:177], v[56:59]
	s_addk_i32 s44, 0x200
	v_mfma_f32_16x16x32_bf16 v[44:47], v[142:145], v[182:185], v[44:47]
	v_mfma_f32_16x16x32_bf16 v[40:43], v[150:153], v[182:185], v[40:43]
	s_add_u32 s76, s76, 0x100
	s_addc_u32 s77, s77, 0
	v_mfma_f32_16x16x32_bf16 v[28:31], v[142:145], v[190:193], v[28:31]
	v_mfma_f32_16x16x32_bf16 v[24:27], v[150:153], v[190:193], v[24:27]
	v_lshl_add_u64 v[136:137], v[136:137], 0, s[58:59]
	v_mfma_f32_16x16x32_bf16 v[12:15], v[142:145], v[198:201], v[12:15]
	v_mfma_f32_16x16x32_bf16 v[8:11], v[150:153], v[198:201], v[8:11]
	v_lshl_add_u64 v[134:135], v[134:135], 0, s[58:59]
	v_mfma_f32_16x16x32_bf16 v[60:63], v[146:149], v[178:181], v[60:63]
	v_mfma_f32_16x16x32_bf16 v[56:59], v[154:157], v[178:181], v[56:59]
	v_mfma_f32_16x16x32_bf16 v[44:47], v[146:149], v[186:189], v[44:47]
	v_mfma_f32_16x16x32_bf16 v[40:43], v[154:157], v[186:189], v[40:43]
	v_mfma_f32_16x16x32_bf16 v[28:31], v[146:149], v[194:197], v[28:31]
	v_mfma_f32_16x16x32_bf16 v[24:27], v[154:157], v[194:197], v[24:27]
	v_mfma_f32_16x16x32_bf16 v[12:15], v[146:149], v[202:205], v[12:15]
	v_mfma_f32_16x16x32_bf16 v[8:11], v[154:157], v[202:205], v[8:11]
	v_mfma_f32_16x16x32_bf16 v[52:55], v[158:161], v[174:177], v[52:55]
	v_mfma_f32_16x16x32_bf16 v[48:51], v[166:169], v[174:177], v[48:51]
	v_mfma_f32_16x16x32_bf16 v[36:39], v[158:161], v[182:185], v[36:39]
	v_mfma_f32_16x16x32_bf16 v[32:35], v[166:169], v[182:185], v[32:35]
	v_mfma_f32_16x16x32_bf16 v[20:23], v[158:161], v[190:193], v[20:23]
	v_mfma_f32_16x16x32_bf16 v[16:19], v[166:169], v[190:193], v[16:19]
	v_mfma_f32_16x16x32_bf16 v[4:7], v[158:161], v[198:201], v[4:7]
	v_mfma_f32_16x16x32_bf16 v[0:3], v[166:169], v[198:201], v[0:3]
	v_mfma_f32_16x16x32_bf16 v[52:55], v[162:165], v[178:181], v[52:55]
	v_mfma_f32_16x16x32_bf16 v[48:51], v[170:173], v[178:181], v[48:51]
	v_mfma_f32_16x16x32_bf16 v[36:39], v[162:165], v[186:189], v[36:39]
	v_mfma_f32_16x16x32_bf16 v[32:35], v[170:173], v[186:189], v[32:35]
	v_mfma_f32_16x16x32_bf16 v[20:23], v[162:165], v[194:197], v[20:23]
	v_mfma_f32_16x16x32_bf16 v[16:19], v[170:173], v[194:197], v[16:19]
	v_mfma_f32_16x16x32_bf16 v[4:7], v[162:165], v[202:205], v[4:7]
	v_mfma_f32_16x16x32_bf16 v[0:3], v[170:173], v[202:205], v[0:3]
	s_barrier
	s_add_i32 s22, s82, 2
	s_cmp_gt_u32 s82, 29
	s_cbranch_scc1 .LBB0_1261
	s_mov_b32 s82, s22
	s_branch .LBB0_1257
